# v11 + V^T GEMM epilogue (EpiVT): 32 dwordx2 stores per lane per tile widened to 16 dwordx4 via v_permlane16_swap pairs
# speedup vs baseline: 1.0147x; 1.0147x over previous
.LBB0_1399:
	v_lshl_or_b32 v148, s7, 8, v171
	v_ashrrev_i32_e32 v149, 31, v148
	v_lshl_add_u64 v[144:145], v[148:149], 2, s[18:19]
	flat_load_dwordx4 v[176:179], v[144:145]
	s_lshl_b32 s7, s7, 7
	s_lshl_b32 s6, s6, 8
	s_and_b32 s7, s7, 0xfffff800
	s_add_i32 s7, s7, s6
	v_add_u32_e32 v138, s7, v168
	v_or_b32_e32 v140, 16, v138
	v_ashrrev_i32_e32 v139, 31, v138
	v_ashrrev_i32_e32 v141, 31, v140
	v_mov_b64_e32 v[142:143], s[40:41]
	v_lshlrev_b64 v[156:157], 13, v[138:139]
	v_lshlrev_b64 v[140:141], 13, v[140:141]
	v_lshl_add_u64 v[158:159], s[20:21], 0, v[156:157]
	v_lshl_add_u64 v[156:157], s[20:21], 0, v[140:141]
	v_or_b32_e32 v146, 32, v138
	v_or_b32_e32 v150, 48, v138
	v_add_u32_e32 v152, 0x80, v138
	v_add_u32_e32 v154, 0x90, v138
	v_and_or_b32 v136, v148, s68, v170
	v_ashrrev_i32_e32 v147, 31, v146
	v_ashrrev_i32_e32 v151, 31, v150
	v_ashrrev_i32_e32 v153, 31, v152
	v_ashrrev_i32_e32 v155, 31, v154
	v_lshlrev_b32_e32 v136, 1, v136
	v_lshlrev_b64 v[146:147], 13, v[146:147]
	v_lshlrev_b64 v[150:151], 13, v[150:151]
	v_lshlrev_b64 v[162:163], 13, v[152:153]
	v_lshlrev_b64 v[164:165], 13, v[154:155]
	v_lshl_add_u64 v[160:161], v[158:159], 0, v[136:137]
	v_lshl_add_u64 v[154:155], s[20:21], 0, v[146:147]
	v_lshl_add_u64 v[152:153], s[20:21], 0, v[150:151]
	v_lshl_add_u64 v[150:151], s[20:21], 0, v[162:163]
	v_lshl_add_u64 v[146:147], s[20:21], 0, v[164:165]
	v_lshl_add_u64 v[162:163], v[156:157], 0, v[136:137]
	v_lshl_add_u64 v[164:165], v[154:155], 0, v[136:137]
	v_lshl_add_u64 v[166:167], v[152:153], 0, v[136:137]
	v_lshl_add_u64 v[180:181], v[146:147], 0, v[136:137]
	s_waitcnt vmcnt(0) lgkmcnt(0)
	v_pk_fma_f32 v[140:141], v[176:177], s[38:39], v[142:143] op_sel_hi:[1,0,0]
	v_pk_fma_f32 v[176:177], v[178:179], s[38:39], v[142:143] op_sel_hi:[1,0,0]
	v_mul_f32_e32 v139, 0x4b800000, v140
	v_mul_f32_e32 v149, 0x4b800000, v141
	v_mul_f32_e32 v175, 0x4b800000, v176
	v_mul_f32_e32 v178, 0x4b800000, v177
	v_cmp_gt_f32_e32 vcc, s69, v140
	v_cmp_gt_f32_e64 s[6:7], s69, v141
	v_cmp_gt_f32_e64 s[8:9], s69, v176
	v_cmp_gt_f32_e64 s[12:13], s69, v177
	v_cndmask_b32_e32 v139, v140, v139, vcc
	v_cndmask_b32_e64 v141, v141, v149, s[6:7]
	v_cndmask_b32_e64 v149, v176, v175, s[8:9]
	v_cndmask_b32_e64 v175, v177, v178, s[12:13]
	v_rsq_f32_e32 v140, v139
	v_rsq_f32_e32 v141, v141
	v_rsq_f32_e32 v176, v149
	v_rsq_f32_e32 v177, v175
	v_lshl_add_u64 v[178:179], v[150:151], 0, v[136:137]
	v_pk_mul_f32 v[182:183], v[140:141], s[42:43] op_sel_hi:[1,0]
	v_pk_mul_f32 v[184:185], v[176:177], s[42:43] op_sel_hi:[1,0]
	v_cndmask_b32_e64 v141, v141, v183, s[6:7]
	v_cndmask_b32_e32 v140, v140, v182, vcc
	v_cndmask_b32_e64 v177, v177, v185, s[12:13]
	v_cndmask_b32_e64 v176, v176, v184, s[8:9]
	v_pk_mul_f32 v[98:99], v[98:99], v[176:177]
	v_pk_mul_f32 v[96:97], v[96:97], v[140:141]
	v_pk_mul_f32 v[102:103], v[102:103], v[176:177]
	v_pk_mul_f32 v[100:101], v[100:101], v[140:141]
	v_pk_mul_f32 v[106:107], v[106:107], v[176:177]
	v_pk_mul_f32 v[104:105], v[104:105], v[140:141]
	v_pk_mul_f32 v[110:111], v[110:111], v[176:177]
	v_pk_mul_f32 v[108:109], v[108:109], v[140:141]
	v_pk_mul_f32 v[122:123], v[122:123], v[176:177]
	v_pk_mul_f32 v[120:121], v[120:121], v[140:141]
	v_pk_mul_f32 v[126:127], v[126:127], v[176:177]
	v_pk_mul_f32 v[124:125], v[124:125], v[140:141]
	v_cvt_pk_bf16_f32 v192, v96, v97
	v_cvt_pk_bf16_f32 v193, v98, v99
	v_cvt_pk_bf16_f32 v196, v100, v101
	v_cvt_pk_bf16_f32 v197, v102, v103
	v_cvt_pk_bf16_f32 v200, v104, v105
	v_cvt_pk_bf16_f32 v201, v106, v107
	v_cvt_pk_bf16_f32 v204, v108, v109
	v_cvt_pk_bf16_f32 v205, v110, v111
	v_cvt_pk_bf16_f32 v208, v120, v121
	v_cvt_pk_bf16_f32 v209, v122, v123
	v_cvt_pk_bf16_f32 v212, v124, v125
	v_cvt_pk_bf16_f32 v213, v126, v127
	v_pk_mul_f32 v[96:97], v[118:119], v[176:177]
	v_pk_mul_f32 v[98:99], v[116:117], v[140:141]
	v_pk_mul_f32 v[100:101], v[112:113], v[140:141]
	v_cvt_pk_bf16_f32 v232, v98, v99
	v_cvt_pk_bf16_f32 v233, v96, v97
	v_add_u32_e32 v96, 0xa0, v138
	v_ashrrev_i32_e32 v97, 31, v96
	v_lshlrev_b64 v[96:97], 13, v[96:97]
	v_lshl_add_u64 v[96:97], s[20:21], 0, v[96:97]
	v_lshl_add_u64 v[104:105], v[96:97], 0, v[136:137]
	v_pk_mul_f32 v[98:99], v[114:115], v[176:177]
	v_cvt_pk_bf16_f32 v236, v100, v101
	v_cvt_pk_bf16_f32 v237, v98, v99
	v_add_u32_e32 v98, 0xb0, v138
	v_ashrrev_i32_e32 v99, 31, v98
	v_lshlrev_b64 v[98:99], 13, v[98:99]
	v_lshl_add_u64 v[98:99], s[20:21], 0, v[98:99]
	v_lshl_add_u64 v[106:107], v[98:99], 0, v[136:137]
	flat_load_dwordx4 v[100:103], v[144:145] offset:16
	v_or_b32_e32 v108, 0x80, v148
	s_waitcnt vmcnt(0) lgkmcnt(0)
	v_pk_fma_f32 v[100:101], v[100:101], s[38:39], v[142:143] op_sel_hi:[1,0,0]
	v_pk_fma_f32 v[102:103], v[102:103], s[38:39], v[142:143] op_sel_hi:[1,0,0]
	v_mul_f32_e32 v109, 0x4b800000, v100
	v_mul_f32_e32 v110, 0x4b800000, v101
	v_mul_f32_e32 v111, 0x4b800000, v102
	v_mul_f32_e32 v112, 0x4b800000, v103
	v_cmp_gt_f32_e32 vcc, s69, v100
	v_cmp_gt_f32_e64 s[6:7], s69, v101
	v_cmp_gt_f32_e64 s[8:9], s69, v102
	v_cmp_gt_f32_e64 s[12:13], s69, v103
	v_cndmask_b32_e32 v100, v100, v109, vcc
	v_cndmask_b32_e64 v101, v101, v110, s[6:7]
	v_cndmask_b32_e64 v102, v102, v111, s[8:9]
	v_cndmask_b32_e64 v103, v103, v112, s[12:13]
	v_rsq_f32_e32 v100, v100
	v_rsq_f32_e32 v101, v101
	v_rsq_f32_e32 v102, v102
	v_rsq_f32_e32 v103, v103
	v_ashrrev_i32_e32 v109, 31, v108
	v_pk_mul_f32 v[112:113], v[100:101], s[42:43] op_sel_hi:[1,0]
	v_lshl_add_u64 v[110:111], v[108:109], 2, s[18:19]
	v_pk_mul_f32 v[114:115], v[102:103], s[42:43] op_sel_hi:[1,0]
	v_cndmask_b32_e64 v101, v101, v113, s[6:7]
	v_cndmask_b32_e32 v100, v100, v112, vcc
	v_cndmask_b32_e64 v103, v103, v115, s[12:13]
	v_cndmask_b32_e64 v102, v102, v114, s[8:9]
	v_pk_mul_f32 v[66:67], v[66:67], v[102:103]
	v_pk_mul_f32 v[64:65], v[64:65], v[100:101]
	v_pk_mul_f32 v[70:71], v[70:71], v[102:103]
	v_pk_mul_f32 v[68:69], v[68:69], v[100:101]
	v_pk_mul_f32 v[74:75], v[74:75], v[102:103]
	v_pk_mul_f32 v[72:73], v[72:73], v[100:101]
	v_pk_mul_f32 v[78:79], v[78:79], v[102:103]
	v_pk_mul_f32 v[76:77], v[76:77], v[100:101]
	v_pk_mul_f32 v[82:83], v[82:83], v[102:103]
	v_pk_mul_f32 v[80:81], v[80:81], v[100:101]
	v_pk_mul_f32 v[86:87], v[86:87], v[102:103]
	v_pk_mul_f32 v[84:85], v[84:85], v[100:101]
	v_pk_mul_f32 v[90:91], v[90:91], v[102:103]
	v_pk_mul_f32 v[88:89], v[88:89], v[100:101]
	v_pk_mul_f32 v[94:95], v[94:95], v[102:103]
	v_pk_mul_f32 v[92:93], v[92:93], v[100:101]
	v_cvt_pk_bf16_f32 v194, v64, v65
	v_cvt_pk_bf16_f32 v195, v66, v67
	v_cvt_pk_bf16_f32 v198, v68, v69
	v_cvt_pk_bf16_f32 v199, v70, v71
	v_cvt_pk_bf16_f32 v202, v72, v73
	v_cvt_pk_bf16_f32 v203, v74, v75
	v_cvt_pk_bf16_f32 v206, v76, v77
	v_cvt_pk_bf16_f32 v207, v78, v79
	v_cvt_pk_bf16_f32 v210, v80, v81
	v_cvt_pk_bf16_f32 v211, v82, v83
	v_cvt_pk_bf16_f32 v214, v84, v85
	v_cvt_pk_bf16_f32 v215, v86, v87
	v_cvt_pk_bf16_f32 v234, v88, v89
	v_cvt_pk_bf16_f32 v235, v90, v91
	v_cvt_pk_bf16_f32 v238, v92, v93
	v_cvt_pk_bf16_f32 v239, v94, v95
	v_mbcnt_lo_u32_b32 v240, -1, 0
	v_mbcnt_hi_u32_b32 v240, -1, v240
	v_and_b32_e32 v240, 16, v240
	v_lshrrev_b32_e32 v240, 1, v240
	v_mov_b32_e32 v241, 0
	v_lshl_add_u64 v[160:161], v[160:161], 0, v[240:241]
	v_lshl_add_u64 v[162:163], v[162:163], 0, v[240:241]
	v_lshl_add_u64 v[164:165], v[164:165], 0, v[240:241]
	v_lshl_add_u64 v[166:167], v[166:167], 0, v[240:241]
	v_lshl_add_u64 v[178:179], v[178:179], 0, v[240:241]
	v_lshl_add_u64 v[180:181], v[180:181], 0, v[240:241]
	v_lshl_add_u64 v[104:105], v[104:105], 0, v[240:241]
	v_lshl_add_u64 v[106:107], v[106:107], 0, v[240:241]
	v_permlane16_swap_b32_e32 v192, v194
	v_permlane16_swap_b32_e32 v193, v195
	v_permlane16_swap_b32_e32 v196, v198
	v_permlane16_swap_b32_e32 v197, v199
	v_permlane16_swap_b32_e32 v200, v202
	v_permlane16_swap_b32_e32 v201, v203
	v_permlane16_swap_b32_e32 v204, v206
	v_permlane16_swap_b32_e32 v205, v207
	v_permlane16_swap_b32_e32 v208, v210
	v_permlane16_swap_b32_e32 v209, v211
	v_permlane16_swap_b32_e32 v212, v214
	v_permlane16_swap_b32_e32 v213, v215
	v_permlane16_swap_b32_e32 v232, v234
	v_permlane16_swap_b32_e32 v233, v235
	v_permlane16_swap_b32_e32 v236, v238
	v_permlane16_swap_b32_e32 v237, v239
	flat_store_dwordx4 v[160:161], v[192:195]
	flat_store_dwordx4 v[162:163], v[196:199]
	flat_store_dwordx4 v[164:165], v[200:203]
	flat_store_dwordx4 v[166:167], v[204:207]
	flat_store_dwordx4 v[178:179], v[208:211]
	flat_store_dwordx4 v[180:181], v[212:215]
	flat_store_dwordx4 v[104:105], v[232:235]
	flat_store_dwordx4 v[106:107], v[236:239]
	flat_load_dwordx4 v[76:79], v[110:111]
	v_and_or_b32 v64, v108, s73, v170
	v_lshlrev_b32_e32 v136, 1, v64
	v_lshl_add_u64 v[64:65], v[158:159], 0, v[136:137]
	v_lshl_add_u64 v[66:67], v[156:157], 0, v[136:137]
	v_lshl_add_u64 v[68:69], v[154:155], 0, v[136:137]
	v_lshl_add_u64 v[70:71], v[152:153], 0, v[136:137]
	v_lshl_add_u64 v[72:73], v[150:151], 0, v[136:137]
	v_lshl_add_u64 v[74:75], v[146:147], 0, v[136:137]
	s_waitcnt vmcnt(0) lgkmcnt(0)
	v_pk_fma_f32 v[76:77], v[76:77], s[38:39], v[142:143] op_sel_hi:[1,0,0]
	v_pk_fma_f32 v[78:79], v[78:79], s[38:39], v[142:143] op_sel_hi:[1,0,0]
	v_mul_f32_e32 v80, 0x4b800000, v76
	v_mul_f32_e32 v81, 0x4b800000, v77
	v_mul_f32_e32 v82, 0x4b800000, v78
	v_mul_f32_e32 v83, 0x4b800000, v79
	v_cmp_gt_f32_e32 vcc, s69, v76
	v_cmp_gt_f32_e64 s[6:7], s69, v77
	v_cmp_gt_f32_e64 s[8:9], s69, v78
	v_cmp_gt_f32_e64 s[12:13], s69, v79
	v_cndmask_b32_e32 v76, v76, v80, vcc
	v_cndmask_b32_e64 v77, v77, v81, s[6:7]
	v_cndmask_b32_e64 v78, v78, v82, s[8:9]
	v_cndmask_b32_e64 v79, v79, v83, s[12:13]
	v_rsq_f32_e32 v76, v76
	v_rsq_f32_e32 v77, v77
	v_rsq_f32_e32 v78, v78
	v_rsq_f32_e32 v79, v79
	v_lshl_add_u64 v[80:81], v[96:97], 0, v[136:137]
	v_pk_mul_f32 v[84:85], v[76:77], s[42:43] op_sel_hi:[1,0]
	v_lshl_add_u64 v[82:83], v[98:99], 0, v[136:137]
	v_pk_mul_f32 v[86:87], v[78:79], s[42:43] op_sel_hi:[1,0]
	v_cndmask_b32_e64 v77, v77, v85, s[6:7]
	v_cndmask_b32_e32 v76, v76, v84, vcc
	v_cndmask_b32_e64 v79, v79, v87, s[12:13]
	v_cndmask_b32_e64 v78, v78, v86, s[8:9]
	v_pk_mul_f32 v[34:35], v[34:35], v[78:79]
	v_pk_mul_f32 v[32:33], v[32:33], v[76:77]
	v_pk_mul_f32 v[38:39], v[38:39], v[78:79]
	v_pk_mul_f32 v[36:37], v[36:37], v[76:77]
	v_pk_mul_f32 v[42:43], v[42:43], v[78:79]
	v_pk_mul_f32 v[40:41], v[40:41], v[76:77]
	v_pk_mul_f32 v[46:47], v[46:47], v[78:79]
	v_pk_mul_f32 v[44:45], v[44:45], v[76:77]
	v_pk_mul_f32 v[50:51], v[50:51], v[78:79]
	v_pk_mul_f32 v[48:49], v[48:49], v[76:77]
	v_pk_mul_f32 v[54:55], v[54:55], v[78:79]
	v_pk_mul_f32 v[52:53], v[52:53], v[76:77]
	v_pk_mul_f32 v[58:59], v[58:59], v[78:79]
	v_pk_mul_f32 v[56:57], v[56:57], v[76:77]
	v_pk_mul_f32 v[62:63], v[62:63], v[78:79]
	v_pk_mul_f32 v[60:61], v[60:61], v[76:77]
	v_cvt_pk_bf16_f32 v96, v32, v33
	v_cvt_pk_bf16_f32 v97, v34, v35
	v_cvt_pk_bf16_f32 v100, v36, v37
	v_cvt_pk_bf16_f32 v101, v38, v39
	v_cvt_pk_bf16_f32 v104, v40, v41
	v_cvt_pk_bf16_f32 v105, v42, v43
	v_cvt_pk_bf16_f32 v108, v44, v45
	v_cvt_pk_bf16_f32 v109, v46, v47
	v_cvt_pk_bf16_f32 v112, v48, v49
	v_cvt_pk_bf16_f32 v113, v50, v51
	v_cvt_pk_bf16_f32 v116, v52, v53
	v_cvt_pk_bf16_f32 v117, v54, v55
	v_cvt_pk_bf16_f32 v120, v56, v57
	v_cvt_pk_bf16_f32 v121, v58, v59
	v_cvt_pk_bf16_f32 v124, v60, v61
	v_cvt_pk_bf16_f32 v125, v62, v63
	flat_load_dwordx4 v[32:35], v[144:145] offset:528
	s_andn2_b64 vcc, exec, s[4:5]
	s_mov_b64 s[4:5], -1
	s_waitcnt vmcnt(0) lgkmcnt(0)
	v_pk_fma_f32 v[32:33], v[32:33], s[38:39], v[142:143] op_sel_hi:[1,0,0]
	v_pk_fma_f32 v[34:35], v[34:35], s[38:39], v[142:143] op_sel_hi:[1,0,0]
	v_mul_f32_e32 v36, 0x4b800000, v32
	v_mul_f32_e32 v37, 0x4b800000, v33
	v_mul_f32_e32 v38, 0x4b800000, v34
	v_mul_f32_e32 v39, 0x4b800000, v35
	v_cmp_gt_f32_e64 s[6:7], s69, v32
	v_cmp_gt_f32_e64 s[8:9], s69, v33
	v_cmp_gt_f32_e64 s[12:13], s69, v34
	v_cmp_gt_f32_e64 s[14:15], s69, v35
	v_cndmask_b32_e64 v32, v32, v36, s[6:7]
	v_cndmask_b32_e64 v33, v33, v37, s[8:9]
	v_cndmask_b32_e64 v34, v34, v38, s[12:13]
	v_cndmask_b32_e64 v35, v35, v39, s[14:15]
	v_rsq_f32_e32 v32, v32
	v_rsq_f32_e32 v33, v33
	v_rsq_f32_e32 v34, v34
	v_rsq_f32_e32 v35, v35
	v_pk_mul_f32 v[36:37], v[32:33], s[42:43] op_sel_hi:[1,0]
	s_nop 0
	v_cndmask_b32_e64 v33, v33, v37, s[8:9]
	v_pk_mul_f32 v[38:39], v[34:35], s[42:43] op_sel_hi:[1,0]
	v_cndmask_b32_e64 v32, v32, v36, s[6:7]
	v_cndmask_b32_e64 v35, v35, v39, s[14:15]
	v_cndmask_b32_e64 v34, v34, v38, s[12:13]
	v_pk_mul_f32 v[2:3], v[2:3], v[34:35]
	v_pk_mul_f32 v[0:1], v[0:1], v[32:33]
	v_pk_mul_f32 v[6:7], v[6:7], v[34:35]
	v_pk_mul_f32 v[4:5], v[4:5], v[32:33]
	v_pk_mul_f32 v[10:11], v[10:11], v[34:35]
	v_pk_mul_f32 v[8:9], v[8:9], v[32:33]
	v_pk_mul_f32 v[14:15], v[14:15], v[34:35]
	v_pk_mul_f32 v[12:13], v[12:13], v[32:33]
	v_pk_mul_f32 v[18:19], v[18:19], v[34:35]
	v_pk_mul_f32 v[16:17], v[16:17], v[32:33]
	v_pk_mul_f32 v[22:23], v[22:23], v[34:35]
	v_pk_mul_f32 v[20:21], v[20:21], v[32:33]
	v_pk_mul_f32 v[26:27], v[26:27], v[34:35]
	v_pk_mul_f32 v[24:25], v[24:25], v[32:33]
	v_pk_mul_f32 v[30:31], v[30:31], v[34:35]
	v_pk_mul_f32 v[28:29], v[28:29], v[32:33]
	v_cvt_pk_bf16_f32 v98, v0, v1
	v_cvt_pk_bf16_f32 v99, v2, v3
	v_cvt_pk_bf16_f32 v102, v4, v5
	v_cvt_pk_bf16_f32 v103, v6, v7
	v_cvt_pk_bf16_f32 v106, v8, v9
	v_cvt_pk_bf16_f32 v107, v10, v11
	v_cvt_pk_bf16_f32 v110, v12, v13
	v_cvt_pk_bf16_f32 v111, v14, v15
	v_cvt_pk_bf16_f32 v114, v16, v17
	v_cvt_pk_bf16_f32 v115, v18, v19
	v_cvt_pk_bf16_f32 v118, v20, v21
	v_cvt_pk_bf16_f32 v119, v22, v23
	v_cvt_pk_bf16_f32 v122, v24, v25
	v_cvt_pk_bf16_f32 v123, v26, v27
	v_cvt_pk_bf16_f32 v126, v28, v29
	v_cvt_pk_bf16_f32 v127, v30, v31
	v_mbcnt_lo_u32_b32 v84, -1, 0
	v_mbcnt_hi_u32_b32 v84, -1, v84
	v_and_b32_e32 v84, 16, v84
	v_lshrrev_b32_e32 v84, 1, v84
	v_mov_b32_e32 v85, 0
	v_lshl_add_u64 v[64:65], v[64:65], 0, v[84:85]
	v_lshl_add_u64 v[66:67], v[66:67], 0, v[84:85]
	v_lshl_add_u64 v[68:69], v[68:69], 0, v[84:85]
	v_lshl_add_u64 v[70:71], v[70:71], 0, v[84:85]
	v_lshl_add_u64 v[72:73], v[72:73], 0, v[84:85]
	v_lshl_add_u64 v[74:75], v[74:75], 0, v[84:85]
	v_lshl_add_u64 v[80:81], v[80:81], 0, v[84:85]
	v_lshl_add_u64 v[82:83], v[82:83], 0, v[84:85]
	v_permlane16_swap_b32_e32 v96, v98
	v_permlane16_swap_b32_e32 v97, v99
	v_permlane16_swap_b32_e32 v100, v102
	v_permlane16_swap_b32_e32 v101, v103
	v_permlane16_swap_b32_e32 v104, v106
	v_permlane16_swap_b32_e32 v105, v107
	v_permlane16_swap_b32_e32 v108, v110
	v_permlane16_swap_b32_e32 v109, v111
	v_permlane16_swap_b32_e32 v112, v114
	v_permlane16_swap_b32_e32 v113, v115
	v_permlane16_swap_b32_e32 v116, v118
	v_permlane16_swap_b32_e32 v117, v119
	v_permlane16_swap_b32_e32 v120, v122
	v_permlane16_swap_b32_e32 v121, v123
	v_permlane16_swap_b32_e32 v124, v126
	v_permlane16_swap_b32_e32 v125, v127
	flat_store_dwordx4 v[64:65], v[96:99]
	flat_store_dwordx4 v[66:67], v[100:103]
	flat_store_dwordx4 v[68:69], v[104:107]
	flat_store_dwordx4 v[70:71], v[108:111]
	flat_store_dwordx4 v[72:73], v[112:115]
	flat_store_dwordx4 v[74:75], v[116:119]
	flat_store_dwordx4 v[80:81], v[120:123]
	flat_store_dwordx4 v[82:83], v[124:127]
	s_cbranch_vccnz .LBB0_1390
	s_andn2_b64 vcc, exec, s[16:17]
	s_cbranch_vccnz .LBB0_1389
	s_barrier
	s_branch .LBB0_1389
